# P3/P5 exchange: no L1 invalidate behind the arrival spin (partials are sc1 loads)
# baseline (speedup 1.0000x reference)
.LBB0_391:
	global_load_dword v167, v213, s[10:11] sc1
	s_waitcnt vmcnt(0)
	v_readfirstlane_b32 s27, v167
	s_cmp_gt_u32 s27, 31
	s_cselect_b64 s[48:49], -1, 0
	s_add_i32 s47, s26, 1
	s_cmp_gt_u32 s26, 0x3fffff
	s_cselect_b64 s[26:27], -1, 0
	s_or_b64 s[26:27], s[48:49], s[26:27]
	s_andn2_b64 vcc, exec, s[26:27]
	s_mov_b32 s26, s47
	s_cbranch_vccnz .LBB0_391
.LBB0_393:
	s_waitcnt vmcnt(0) lgkmcnt(0)
	s_barrier
	s_and_saveexec_b64 s[26:27], s[6:7]
	s_cbranch_execz .LBB0_395
	v_lshl_add_u64 v[164:165], v[164:165], 4, s[14:15]
	global_load_dword v167, v[164:165], off sc1
	global_load_dword v168, v[164:165], off offset:4 sc1
	global_load_dword v169, v[164:165], off offset:8 sc1
	s_nop 0
	global_load_dword v164, v[164:165], off offset:12 sc1
	s_waitcnt vmcnt(0)
	v_add_f32_e32 v165, 0, v167
	v_add_f32_e32 v165, v165, v168
	v_add_f32_e32 v165, v165, v169
	v_add_f32_e32 v164, v165, v164
	v_fmamk_f32 v164, v164, 0x3a800000, v230
	v_mul_f32_e32 v165, 0x4f800000, v164
	v_cmp_gt_f32_e32 vcc, s57, v164
	s_nop 1
	v_cndmask_b32_e32 v164, v164, v165, vcc
	v_sqrt_f32_e32 v165, v164
	s_nop 0
	v_add_u32_e32 v167, -1, v165
	v_add_u32_e32 v168, 1, v165
	v_fma_f32 v169, -v167, v165, v164
	v_fma_f32 v170, -v168, v165, v164
	v_cmp_ge_f32_e64 s[10:11], 0, v169
	s_nop 1
	v_cndmask_b32_e64 v165, v165, v167, s[10:11]
	v_cmp_lt_f32_e64 s[10:11], 0, v170
	s_nop 1
	v_cndmask_b32_e64 v165, v165, v168, s[10:11]
	v_mul_f32_e32 v167, 0x37800000, v165
	v_cndmask_b32_e32 v165, v165, v167, vcc
	v_cmp_class_f32_e32 vcc, v164, v231
	s_nop 1
	v_cndmask_b32_e32 v164, v165, v164, vcc
	v_div_scale_f32 v165, s[10:11], v164, v164, 1.0
	v_rcp_f32_e32 v167, v165
	v_div_scale_f32 v168, vcc, 1.0, v164, 1.0
	v_fma_f32 v169, -v165, v167, 1.0
	v_fmac_f32_e32 v167, v169, v167
	v_mul_f32_e32 v169, v168, v167
	v_fma_f32 v170, -v165, v169, v168
	v_fmac_f32_e32 v169, v170, v167
	v_fma_f32 v165, -v165, v169, v168
	v_div_fmas_f32 v165, v165, v167, v169
	v_div_fixup_f32 v164, v165, v164, 1.0
	v_lshl_add_u32 v165, v166, 2, 0
	ds_write_b32 v165, v164 offset:4096

.LBB0_625:
	global_load_dword v188, v213, s[8:9] sc1
	s_waitcnt vmcnt(0)
	v_readfirstlane_b32 s10, v188
	s_cmp_gt_u32 s10, 31
	s_cselect_b64 s[10:11], -1, 0
	s_add_i32 s19, s3, 1
	s_cmp_gt_u32 s3, 0x3fffff
	s_cselect_b64 s[20:21], -1, 0
	s_or_b64 s[10:11], s[10:11], s[20:21]
	s_andn2_b64 vcc, exec, s[10:11]
	s_mov_b32 s3, s19
	s_cbranch_vccnz .LBB0_625
	s_waitcnt lgkmcnt(0)
.LBB0_627:
	s_waitcnt vmcnt(0) lgkmcnt(0)
	s_barrier
	s_and_saveexec_b64 s[8:9], s[0:1]
	s_cbranch_execz .LBB0_587
	v_lshl_add_u64 v[182:183], v[182:183], 4, s[14:15]
	global_load_dword v188, v[182:183], off sc1
	s_waitcnt lgkmcnt(0)
	global_load_dword v190, v[182:183], off offset:4 sc1
	global_load_dword v191, v[182:183], off offset:8 sc1
	s_nop 0
	global_load_dword v182, v[182:183], off offset:12 sc1
	s_waitcnt vmcnt(0)
	v_add_f32_e32 v183, 0, v188
	v_add_f32_e32 v183, v183, v190
	v_add_f32_e32 v183, v183, v191
	v_add_f32_e32 v182, v183, v182
	v_mov_b32_e32 v183, 0x358637bd
	v_fmamk_f32 v182, v182, 0x3a800000, v183
	v_mul_f32_e32 v183, 0x4f800000, v182
	v_cmp_gt_f32_e32 vcc, s35, v182
	s_nop 1
	v_cndmask_b32_e32 v182, v182, v183, vcc
	v_sqrt_f32_e32 v183, v182
	s_nop 0
	v_add_u32_e32 v188, -1, v183
	v_add_u32_e32 v190, 1, v183
	v_fma_f32 v191, -v188, v183, v182
	v_fma_f32 v192, -v190, v183, v182
	v_cmp_ge_f32_e64 s[0:1], 0, v191
	s_nop 1
	v_cndmask_b32_e64 v183, v183, v188, s[0:1]
	v_cmp_lt_f32_e64 s[0:1], 0, v192
	s_nop 1
	v_cndmask_b32_e64 v183, v183, v190, s[0:1]
	v_mul_f32_e32 v188, 0x37800000, v183
	v_cndmask_b32_e32 v183, v183, v188, vcc
	v_mov_b32_e32 v188, 0x260
	v_cmp_class_f32_e32 vcc, v182, v188
	s_nop 1
	v_cndmask_b32_e32 v182, v183, v182, vcc
	v_div_scale_f32 v183, s[0:1], v182, v182, 1.0
	v_rcp_f32_e32 v188, v183
	v_div_scale_f32 v190, vcc, 1.0, v182, 1.0
	v_fma_f32 v191, -v183, v188, 1.0
	v_fmac_f32_e32 v188, v191, v188
	v_mul_f32_e32 v191, v190, v188
	v_fma_f32 v192, -v183, v191, v190
	v_fmac_f32_e32 v191, v192, v188
	v_fma_f32 v183, -v183, v191, v190
	v_div_fmas_f32 v183, v183, v188, v191
	v_div_fixup_f32 v182, v183, v182, 1.0
	v_lshl_add_u32 v183, v189, 2, 0
	ds_write_b32 v183, v182 offset:4096
	s_branch .LBB0_587
